# baseline (speedup 1.0000x reference)
;     __host__ __device__ bool next(int i, Unit& u) const {
;         const long L = (long)i * G + c; if (L >= nwg) return false;
;         int wgid = (int)L; { const int q = nwg / NXCD, r = nwg % NXCD, xcd = wgid % NXCD, off = wgid / NXCD; wgid = (xcd < r ? xcd * (q + 1) : r * (q + 1) + (xcd - r) * q) + off; }
;         const int nig = WGM * nN, gid = wgid / nig, fm = gid * WGM, gsz = (nM - fm) < WGM ? (nM - fm) : WGM;
;         u.pm = fm + ((wgid % nig) % gsz); u.pn = (wgid % nig) / gsz; return true;
;     }
; template <class Epi, class Sched, bool ALIGN_EPI = false, bool SP2 = false>
; __device__ __forceinline__ void gemm_phase(PG8_LAS unsigned char* lds, const Gemm g, const Sched& S, const Epi& E) {
;     int tid_ = threadIdx.x; asm volatile("" : "+v"(tid_));
;     const int tid = tid_, wid = __builtin_amdgcn_readfirstlane(tid >> 6), lane = tid & 63, wr = wid >> 2, wc = wid & 3, fr = lane & 15, fq = lane >> 4;
;     const int K = g.ld, nt = g.K / BK;
;     unsigned voffA[2], voffB[2];
; #pragma unroll
;     for (int i = 0; i < 2; ++i) { int R, C; stage_rc(tid * 16 + i * 8192, R, C); const int Rb = Epi::PERM ? ((R & ~31) + perm32(R & 31)) : R;
;         voffA[i] = (unsigned)(R * g.lda + C) * 2u; voffB[i] = (unsigned)(Rb * K + C) * 2u; }
;     const size_t kstep = (size_t)(BK * 2);
;     const size_t hstep = (size_t)HALF * K * 2;
;     const size_t tstep = 2 * hstep;
;     const size_t hstepA = (size_t)HALF * g.lda * 2, tstepA = 2 * hstepA, apair = g.a_pair;
;     const unsigned ldsw = (unsigned)wid * 1024u;
;     const int aoff = lds_byte(wr * 64 + fr, fq * 8), boff = lds_byte(wc * 32 + fr, fq * 8);
;     ...
;     Unit cur, nxt; int ui = 0;
;     if (!S.next(0, cur)) return;
;     f32x4 acc[2][2][4][2];
; #pragma unroll
;     for (int a = 0; a < 2; ++a)
; #pragma unroll
;         for (int b = 0; b < 2; ++b)
; #pragma unroll
;             for (int m = 0; m < 4; ++m)
; #pragma unroll
;                 for (int n = 0; n < 2; ++n) acc[a][b][m][n] = (f32x4){0.f, 0.f, 0.f, 0.f};
;     bf16x8 At[4][2], B0[2][2], B1[2][2];
;     const char* cA = (const char*)g.A + (size_t)cur.pm * tstepA; const char* cB = (const char*)g.Bt + (size_t)cur.pn * tstep;
;     S.a_ready(cur, 0);
;     if constexpr (SP2) {
;         PG8_STAGE(PG8_SB(0, 0), cB, voffB); PG8_STAGE(PG8_SB(0, 1), cB + hstep, voffB); PG8_STAGE(PG8_SA(0, 0), cA, voffA); PG8_STAGE(PG8_SA(0, 1), cA + hstepA, voffA);
.LBB0_235:
	s_and_b64 s[4:5], s[12:13], exec
	s_movk_i32 s4, 0x88
	s_cselect_b32 s84, 0x80, s4
	s_load_dword s85, s[92:93], 0x0
	s_load_dwordx2 s[8:9], s[56:57], 0x28
	s_load_dwordx2 s[6:7], s[56:57], 0x50
	s_load_dwordx2 s[4:5], s[56:57], 0x70
	s_mul_i32 s60, s84, 28
	v_mov_b32_e32 v15, v168
	s_cmp_lt_i32 s2, s60
	s_cselect_b64 s[10:11], -1, 0
	s_cmp_ge_i32 s2, s60
	v_readfirstlane_b32 s26, v15
	s_cbranch_scc1 .LBB0_237
	s_lshr_b32 s12, s60, 3
	v_readlane_b32 s13, v255, 11
	s_or_b32 s12, s12, s13
	v_readlane_b32 s13, v255, 10
	s_mul_i32 s12, s12, s13
	v_readlane_b32 s13, v255, 8
	s_add_i32 s12, s12, s13
	s_mul_hi_i32 s13, s12, 0x92492493
	s_add_i32 s13, s13, s12
	s_lshr_b32 s16, s13, 31
	s_ashr_i32 s13, s13, 7
	s_add_i32 s13, s13, s16
	s_lshl_b32 s16, s13, 3
	s_mulk_i32 s13, 0xe0
	s_sub_i32 s12, s12, s13
	s_lshr_b32 s20, s12, 3
	s_and_b32 s12, s12, 7
	s_add_i32 s50, s16, s12
	s_cmp_gt_u32 s20, 23
	s_cbranch_scc1 .Lmix_tail1
	s_lshr_b32 s100, s20, 2
	s_lshl_b32 s100, s100, 1
	s_and_b32 s101, s20, 3
	s_add_i32 s100, s100, s101
	s_cmp_gt_u32 s101, 1
	s_cselect_b32 s101, 14, 0
	s_add_i32 s20, s100, s101
	s_branch .Lmix_done1
.Lmix_tail1:
	s_sub_i32 s20, s20, 12
.Lmix_done1:
.LBB0_237:
	s_andn2_b64 vcc, exec, s[10:11]
	s_cbranch_vccnz .LBB0_368
	v_bfe_i32 v3, v15, 27, 1
	v_lshlrev_b32_e32 v2, 4, v15
	v_lshrrev_b32_e32 v3, 22, v3
	v_add_u32_e32 v3, v2, v3
	v_and_b32_e32 v3, 0xfffffc00, v3
	v_sub_u32_e32 v3, v2, v3
	s_lshl_b32 s10, s0, 11
	v_lshrrev_b32_e32 v4, 4, v3
	s_waitcnt lgkmcnt(0)
	s_add_u32 s10, s54, s10
	v_ashrrev_i32_e32 v0, 31, v15
	v_bitop3_b32 v3, v4, v3, 32 bitop3:0x6c
	s_addc_u32 s11, s55, 0
	v_lshrrev_b32_e32 v0, 26, v0
	v_ashrrev_i32_e32 v5, 31, v3
	s_add_u32 s80, s10, 0x5000000
	v_add_u32_e32 v0, v15, v0
	v_lshrrev_b32_e32 v5, 26, v5
	s_addc_u32 s81, s11, 0
	s_ashr_i32 s59, s58, 31
	s_mul_i32 s11, s58, 0xe00000
	v_ashrrev_i32_e32 v0, 6, v0
	v_add_u32_e32 v5, v3, v5
	s_mul_hi_i32 s10, s58, 0xe00000
	s_add_u32 s11, s54, s11
	v_lshlrev_b32_e32 v4, 3, v0
	v_ashrrev_i32_e32 v10, 6, v5
	v_and_b32_e32 v5, 0xc0, v5
	s_addc_u32 s10, s55, s10
	v_and_b32_e32 v4, -16, v4
	v_sub_u32_e32 v3, v3, v5
	s_add_u32 s82, s11, 0x800000
	v_add_u32_e32 v4, v10, v4
	v_ashrrev_i16_sdwa v3, v236, sext(v3) dst_sel:DWORD dst_unused:UNUSED_PAD src0_sel:DWORD src1_sel:BYTE_0
	s_addc_u32 s83, s10, 0
	v_lshlrev_b32_e32 v6, 5, v0
	v_bfe_i32 v11, v3, 0, 16
	v_lshlrev_b32_e32 v3, 1, v4
	v_lshrrev_b32_e32 v5, 2, v4
	v_and_b32_e32 v7, 3, v10
	s_mov_b32 s10, 0x1fffe0
	v_and_b32_e32 v6, 32, v6
	v_and_b32_e32 v3, 24, v3
	v_and_b32_e32 v5, 4, v5
	v_and_or_b32 v7, v4, s10, v7
	v_or3_b32 v3, v7, v5, v3
	v_add_lshl_u32 v5, v6, v11, 1
	v_add_u32_e32 v2, 0x2000, v2
	v_lshl_add_u32 v156, v3, 11, v5
	v_ashrrev_i32_e32 v3, 31, v2
	v_lshrrev_b32_e32 v3, 22, v3
	v_add_u32_e32 v3, v2, v3
	v_ashrrev_i32_e32 v12, 10, v3
	v_mul_i32_i24_e32 v3, 0x400, v12
	v_sub_u32_e32 v2, v2, v3
	v_lshrrev_b32_e32 v3, 4, v2
	v_bitop3_b32 v2, v3, v2, 32 bitop3:0x6c
	v_lshl_add_u32 v154, v4, 11, v5
	v_ashrrev_i32_e32 v4, 31, v2
	v_lshrrev_b32_e32 v4, 26, v4
	v_lshlrev_b32_e32 v3, 3, v12
	v_add_u32_e32 v4, v2, v4
	v_and_b32_e32 v3, -16, v3
	v_ashrrev_i32_e32 v13, 6, v4
	s_ashr_i32 s28, s26, 6
	v_add_u32_e32 v3, v13, v3
	v_and_b32_e32 v4, 0xc0, v4
	v_and_b32_e32 v6, 3, v13
	s_ashr_i32 s51, s50, 31
	s_ashr_i32 s21, s20, 31
	v_sub_u32_e32 v2, v2, v4
	v_and_or_b32 v6, v3, s10, v6
	s_ashr_i32 s27, s26, 8
	s_lshl_b32 s16, s28, 10
	s_lshl_b64 s[10:11], s[50:51], 19
	s_lshl_b64 s[12:13], s[20:21], 19
	v_ashrrev_i16_sdwa v2, v236, sext(v2) dst_sel:DWORD dst_unused:UNUSED_PAD src0_sel:DWORD src1_sel:BYTE_0
	s_add_u32 s12, s82, s12
	v_lshlrev_b32_e32 v5, 5, v12
	v_bfe_i32 v14, v2, 0, 16
	v_lshlrev_b32_e32 v2, 1, v3
	v_lshrrev_b32_e32 v4, 2, v3
	s_addc_u32 s13, s83, s13
	s_add_i32 s17, s16, 0
	v_and_b32_e32 v5, 32, v5
	v_and_b32_e32 v2, 24, v2
	v_and_b32_e32 v4, 4, v4
	s_add_i32 m0, s17, 0x10000
	v_or3_b32 v2, v6, v4, v2
	v_add_lshl_u32 v4, v5, v14, 1
	global_load_lds_dwordx4 v156, s[12:13]
	s_add_i32 m0, s17, 0x12000
	v_lshl_add_u32 v160, v2, 11, v4
	s_add_u32 s42, s12, 0x40000
	global_load_lds_dwordx4 v160, s[12:13]
	s_addc_u32 s43, s13, 0
	s_add_i32 m0, s17, 0x14000
	v_lshl_add_u32 v158, v3, 11, v4
	global_load_lds_dwordx4 v156, s[42:43]
	s_add_i32 m0, s17, 0x16000
	s_add_u32 s10, s80, s10
	s_addc_u32 s11, s81, s11
	s_add_i32 s51, s17, 0x2000
	global_load_lds_dwordx4 v160, s[42:43]
	s_mov_b32 m0, s17
	s_add_u32 s42, s10, 0x40000
	global_load_lds_dwordx4 v154, s[10:11]
	s_mov_b32 m0, s51
	s_addc_u32 s43, s11, 0
	s_add_i32 s35, s17, 0x4000
	global_load_lds_dwordx4 v158, s[10:11]
	s_mov_b32 m0, s35
	s_add_i32 s30, s17, 0x6000
	global_load_lds_dwordx4 v154, s[42:43]
	s_mov_b32 m0, s30
	v_mov_b32_e32 v157, v1
	global_load_lds_dwordx4 v158, s[42:43]
	v_mov_b32_e32 v161, v1
	v_mov_b32_e32 v155, v1
	v_mov_b32_e32 v159, v1
	s_cmp_eq_u32 s27, 1
	v_lshl_add_u64 v[8:9], s[12:13], 0, v[156:157]
	v_lshl_add_u64 v[6:7], s[12:13], 0, v[160:161]
	v_lshl_add_u64 v[2:3], s[10:11], 0, v[154:155]
	s_cselect_b64 s[64:65], -1, 0
	s_cmp_lg_u32 s27, 1
	v_lshl_add_u64 v[4:5], s[10:11], 0, v[158:159]
	s_cbranch_scc1 .LBB0_240
	s_barrier

;     __device__ __forceinline__ bool next(int i, Unit& u) const { if (i > 0) return false; u = u0; return true; }
;     __host__ __device__ bool next(int i, Unit& u) const {
;         const long L = (long)i * G + c; if (L >= nwg) return false;
;         int wgid = (int)L; { const int q = nwg / NXCD, r = nwg % NXCD, xcd = wgid % NXCD, off = wgid / NXCD; wgid = (xcd < r ? xcd * (q + 1) : r * (q + 1) + (xcd - r) * q) + off; }
;         const int nig = WGM * nN, gid = wgid / nig, fm = gid * WGM, gsz = (nM - fm) < WGM ? (nM - fm) : WGM;
;         u.pm = fm + ((wgid % nig) % gsz); u.pn = (wgid % nig) / gsz; return true;
;     }
; template <class Epi, class Sched, bool ALIGN_EPI = false, bool SP2 = false>
; __device__ __forceinline__ void gemm_phase(PG8_LAS unsigned char* lds, const Gemm g, const Sched& S, const Epi& E) {
;     ...
;         const bool has_next = S.next(ui + 1, nxt);
;         const char* nA = has_next ? (const char*)g.A + (size_t)nxt.pm * tstepA : cA; const char* nB = has_next ? (const char*)g.Bt + (size_t)nxt.pn * tstep : cB;
;         for (int t = 0; t < nt; t += 2) {
;             if constexpr (Epi::MIDSCALE) { if (t == (nt >> 1)) E.midscale(acc, cur, wr, fr, ui); }
;             const bool last = (t == nt - 2);
;             const char* a1 = cA + (size_t)(t >> 1) * apair + kstep;
;             const char* a2 = last ? nA : cA + (size_t)((t >> 1) + 1) * apair; const char* b2 = last ? nB : cB + (size_t)(t + 2) * kstep;
;             const char* a3 = a2 + kstep; const char* b3 = b2 + kstep;
;             if (last && has_next) S.a_ready(nxt, ui + 1);
.LBB0_243:
	s_add_i32 s87, s87, 1
	s_mul_i32 s8, s87, s92
	s_mul_hi_u32 s9, s87, s85
	s_add_i32 s9, s9, s8
	s_mul_i32 s8, s87, s85
	s_add_u32 s26, s8, s2
	s_addc_u32 s27, s9, s22
	v_mov_b64_e32 v[2:3], s[60:61]
	v_cmp_ge_i64_e32 vcc, s[26:27], v[2:3]
	v_cmp_lt_i64_e64 s[8:9], s[26:27], v[2:3]
	s_cbranch_vccnz .LBB0_245
	s_ashr_i32 s21, s26, 31
	s_lshr_b32 s21, s21, 29
	s_add_i32 s21, s26, s21
	s_ashr_i32 s27, s21, 3
	s_and_b32 s21, s21, -8
	s_sub_i32 s21, s26, s21
	s_lshr_b32 s26, s21, 31
	s_or_b32 s26, s93, s26
	s_mul_i32 s21, s26, s21
	s_add_i32 s21, s21, s27
	s_mul_hi_i32 s26, s21, 0x92492493
	s_add_i32 s26, s26, s21
	s_lshr_b32 s27, s26, 31
	s_ashr_i32 s26, s26, 7
	s_add_i32 s26, s26, s27
	s_lshl_b32 s27, s26, 3
	s_mulk_i32 s26, 0xe0
	s_sub_i32 s21, s21, s26
	s_lshr_b32 s42, s21, 3
	s_and_b32 s21, s21, 7
	s_add_i32 s62, s21, s27
	s_cmp_gt_u32 s42, 23
	s_cbranch_scc1 .Lmix_tail2
	s_lshr_b32 s100, s42, 2
	s_lshl_b32 s100, s100, 1
	s_and_b32 s101, s42, 3
	s_add_i32 s100, s100, s101
	s_cmp_gt_u32 s101, 1
	s_cselect_b32 s101, 14, 0
	s_add_i32 s42, s100, s101
	s_branch .Lmix_done2
.Lmix_tail2:
	s_sub_i32 s42, s42, 12
.Lmix_done2:
.LBB0_245:
	s_ashr_i32 s63, s62, 31
	s_lshl_b64 s[26:27], s[62:63], 19
	s_add_u32 s52, s80, s26
	s_addc_u32 s53, s81, s27
	s_and_b64 s[26:27], s[8:9], exec
	s_cselect_b32 s21, s53, s11
	s_cselect_b32 s28, s52, s10
	s_ashr_i32 s43, s42, 31
	s_lshl_b64 s[26:27], s[42:43], 19
	s_add_u32 s26, s82, s26
	s_addc_u32 s27, s83, s27
	s_and_b64 s[44:45], s[8:9], exec
	s_cselect_b32 s43, s27, s13
	s_cselect_b32 s46, s26, s12
	s_add_u32 s10, s10, 0x40080
	s_addc_u32 s11, s11, 0
	s_add_u32 s47, s12, 0x100
	v_mov_b32_e32 v2, 0
	s_addc_u32 s63, s13, 0
	s_mov_b32 vcc_lo, -2
	s_waitcnt lgkmcnt(0)
	s_cmp_gt_i32 s20, 15
	s_cbranch_scc1 .Lpf_skip
	s_lshl_b32 s100, s50, 8
	s_add_i32 s101, s100, s0
	s_cmp_gt_i32 s101, 0xffff
	s_cbranch_scc1 .Lpf_skip
	s_lshr_b32 s101, s17, 10
	v_mov_b32_e32 v231, 0
	s_cmp_gt_u32 s101, 3
	s_cbranch_scc1 .Lpf_w
	s_lshl_b32 s101, s101, 6
	s_add_i32 s100, s100, s101
	v_add_u32_e32 v230, s100, v174
	v_lshl_add_u64 v[230:231], v[230:231], 2, s[68:69]
	s_branch .Lpf_go
